# more streamers still: P2 128 and P3 112 streamer workgroups (four-barrier decode loop)
# baseline (speedup 1.0000x reference)
; __device__ __forceinline__ void sb_decode_stream(Frame& F, unsigned* qctr, int base, int limit) {
;     const float* CK = kin(2); const float* CV = kin(3); const int* PT = (const int*)kin(4);
;     int lane = F.lane; asm volatile("" : "+v"(lane));
;     const int half = lane >> 5, l32 = lane & 31;
;     const float k1 = SB_SCALE * 1.4426950408889634f;
;     const size_t lo = (size_t)half * (NH * HD) + 4 * l32;
;     int it;
;     { const unsigned v = __hip_atomic_fetch_add(qctr, 1u, __ATOMIC_RELAXED, __HIP_MEMORY_SCOPE_AGENT);
;       it = (int)(__builtin_amdgcn_readfirstlane(v) >> 6); if (it >= limit) return; it += base; }
; __global__ void __launch_bounds__(NWAVES * 64, 2) hymba_fwd(Args args) {
;     ...
;         const bool streamer = (F.bid % 3) == 0 && F.bid < 252;
;         if (streamer) sb_decode_stream(F, F.ctl + CW_QUEUE, 0, DEC_Q2);
.LBB0_1119:
	s_cmp_lt_i32 s84, 3
	s_cselect_b64 s[2:3], -1, 0
	s_cmp_gt_i32 s85, 2
	s_cselect_b64 s[4:5], -1, 0
	s_and_b64 s[2:3], s[2:3], s[4:5]
	s_andn2_b64 vcc, exec, s[2:3]
	s_cbranch_vccnz .LBB0_1376
	s_lshr_b32 s2, s96, 3
	s_mov_b32 s3, 0xca52d4b5
	s_lshr_b32 s3, s3, s2
	s_and_b32 s3, s3, 1
	s_cmp_eq_u32 s3, 1
	s_cselect_b64 s[42:43], -1, 0
	s_add_u32 s40, s26, 0x1000
	s_addc_u32 s41, s27, 0
	s_add_u32 s38, s26, 0x2ff18000
	s_addc_u32 s39, s27, 0
	s_add_u32 s3, s26, 0x2ff70400
	s_addc_u32 s4, s27, 0
	s_and_b64 vcc, exec, s[42:43]
	s_cbranch_vccz .LBB0_1132
	s_load_dwordx2 s[50:51], s[0:1], 0x10
	s_load_dwordx2 s[52:53], s[0:1], 0x18
	s_load_dwordx2 s[54:55], s[0:1], 0x20
	s_load_dwordx2 s[56:57], s[0:1], 0x60
	s_add_u32 s58, s26, 0x1000
	s_addc_u32 s59, s27, 0
	s_add_u32 s60, s26, 0x2ff18000
	s_addc_u32 s61, s27, 0
	s_add_u32 s62, s26, 0x2ff70400
	s_addc_u32 s63, s27, 0
	s_mov_b32 s76, 0xcccccccc
	s_mov_b32 s77, 0xcccccccc
	s_mov_b32 s78, 0xaaaaaaaa
	s_mov_b32 s79, 0xaaaaaaaa
	v_and_b32_e32 v193, 31, v199
	v_lshrrev_b32_e32 v188, 5, v199
	v_lshlrev_b32_e32 v193, 4, v193
	v_lshl_add_u32 v187, v188, 12, v193
	v_lshlrev_b32_e32 v188, 7, v188
	v_mov_b32_e32 v189, 0
	v_mov_b32_e32 v190, 64
	v_mov_b32_e32 v190, 0x200
	s_mov_b32 s37, 0x251e0
	s_cmp_eq_u32 s94, 0
	s_cbranch_scc0 .Ldqa_pro
	s_mov_b64 exec, 1
	global_atomic_add v191, v189, v190, s[58:59] sc0
	s_mov_b64 exec, -1

; __device__ __forceinline__ void sb_decode_stream(Frame& F, unsigned* qctr, int base, int limit) {
;     const float* CK = kin(2); const float* CV = kin(3); const int* PT = (const int*)kin(4);
;     int lane = F.lane; asm volatile("" : "+v"(lane));
;     const int half = lane >> 5, l32 = lane & 31;
;     const float k1 = SB_SCALE * 1.4426950408889634f;
;     const size_t lo = (size_t)half * (NH * HD) + 4 * l32;
;     int it;
;     { const unsigned v = __hip_atomic_fetch_add(qctr, 1u, __ATOMIC_RELAXED, __HIP_MEMORY_SCOPE_AGENT);
;       it = (int)(__builtin_amdgcn_readfirstlane(v) >> 6); if (it >= limit) return; it += base; }
; __device__ __forceinline__ void p2_mixers(Frame& F, unsigned* qctr) {
;     ...
;     const bool streamer = (F.bid >= NB * NH) && (((F.bid >> 3) - 2) % 5 < 2);
;     if (streamer) sb_decode_stream(F, qctr + 64, DEC_Q2, DEC_ITEMS - DEC_Q2);
.LBB0_1408:
	s_lshr_b32 s2, s96, 3
	s_mov_b32 s3, 0x18c6b1ac
	s_lshr_b32 s3, s3, s2
	s_and_b32 s3, s3, 1
	s_cmp_eq_u32 s3, 0
	s_cselect_b64 s[6:7], -1, 0
	s_add_u32 s38, s26, 0x1100
	s_addc_u32 s39, s27, 0
	s_add_u32 s3, s26, 0x2ff18000
	s_addc_u32 s4, s27, 0
	s_add_u32 s5, s26, 0x2ff70400
	s_addc_u32 s23, s27, 0
	s_or_b64 s[6:7], s[10:11], s[6:7]
	s_andn2_b64 vcc, exec, s[6:7]
	s_cbranch_vccz .LBB0_1420
	s_load_dwordx2 s[50:51], s[0:1], 0x10
	s_load_dwordx2 s[52:53], s[0:1], 0x18
	s_load_dwordx2 s[54:55], s[0:1], 0x20
	s_load_dwordx2 s[56:57], s[0:1], 0x60
	s_add_u32 s58, s26, 0x1100
	s_addc_u32 s59, s27, 0
	s_add_u32 s60, s26, 0x2ff18000
	s_addc_u32 s61, s27, 0
	s_add_u32 s62, s26, 0x2ff70400
	s_addc_u32 s63, s27, 0
	s_mov_b32 s76, 0xcccccccc
	s_mov_b32 s77, 0xcccccccc
	s_mov_b32 s78, 0xaaaaaaaa
	s_mov_b32 s79, 0xaaaaaaaa
	v_and_b32_e32 v193, 31, v199
	v_lshrrev_b32_e32 v188, 5, v199
	v_lshlrev_b32_e32 v193, 4, v193
	v_lshl_add_u32 v187, v188, 12, v193
	v_lshlrev_b32_e32 v188, 7, v188
	v_mov_b32_e32 v189, 0
	v_mov_b32_e32 v190, 64
	v_mov_b32_e32 v190, 0x200
	s_mov_b32 s37, 0x251e0
	s_cmp_eq_u32 s94, 0
	s_cbranch_scc0 .Ldqc_pro
	s_mov_b64 exec, 1
	global_atomic_add v191, v189, v190, s[58:59] sc0
	s_mov_b64 exec, -1
